# mlstm_c: waves 4..7 take lt' = 3 - lt (thread index bits 6,7 flipped for tid >= 256) so each SIMD carries 5 causal blocks instead of 2..8
# speedup vs baseline: 1.0050x; 1.0050x over previous
.Lmc_noat:
	v_mov_b32_e32 v222, v211
	v_lshrrev_b32_e32 v220, 8, v222
	v_mul_u32_u24_e32 v220, 0xc0, v220
	v_xor_b32_e32 v222, v222, v220
	s_and_b32 s5, s30, 63
	v_ashrrev_i32_e32 v220, 6, v222
	s_and_b32 s1, s19, 0xfffff000
	s_lshl_b32 s4, s5, 6
	v_and_b32_e32 v221, 15, v222
	s_waitcnt vmcnt(2)
	v_and_b32_e32 v20, 3, v220
	s_ashr_i32 s0, s30, 6
	s_or_b32 s4, s1, s4
	v_lshl_or_b32 v241, v20, 4, v221
	s_and_b32 s36, s0, 3
	v_or_b32_e32 v218, s4, v241
	s_movk_i32 s1, 0x2800
	v_or_b32_e32 v21, s4, v221
	v_mov_b64_e32 v[18:19], s[92:93]
	v_mad_i64_i32 v[216:217], s[6:7], v218, s1, 0
	s_lshl_b32 s24, s36, 8
	v_mad_i64_i32 v[22:23], s[6:7], v21, s63, v[18:19]
	v_lshl_add_u64 v[2:3], v[216:217], 1, s[28:29]
	v_and_b32_e32 v0, 48, v222
	v_lshl_add_u64 v[22:23], v[22:23], 0, s[24:25]
	v_lshl_add_u64 v[2:3], v[2:3], 0, s[24:25]
	v_lshl_add_u64 v[22:23], v[22:23], 0, v[0:1]
	s_mov_b64 s[8:9], 0x19ca0400
	v_lshl_add_u64 v[2:3], v[2:3], 0, v[0:1]
	s_waitcnt vmcnt(1)
	v_lshl_add_u64 v[24:25], v[22:23], 0, s[8:9]
	v_add_co_u32_e32 v22, vcc, s56, v22
	global_load_dword v223, v1, s[2:3]
	global_load_dwordx4 v[14:17], v[2:3], off
	global_load_dwordx4 v[10:13], v[2:3], off offset:64
	global_load_dwordx4 v[6:9], v[2:3], off offset:128
	s_nop 0
	global_load_dwordx4 v[2:5], v[2:3], off offset:192
	v_addc_co_u32_e32 v23, vcc, 0, v23, vcc
	global_load_dwordx4 v[202:205], v[24:25], off offset:64
	global_load_dwordx4 v[198:201], v[24:25], off offset:128
	global_load_dwordx4 v[206:209], v[22:23], off offset:1024
	global_load_dwordx4 v[194:197], v[24:25], off offset:192
	v_or_b32_e32 v22, 16, v21
	v_mad_i64_i32 v[18:19], s[6:7], v22, s63, v[18:19]
	v_lshl_add_u64 v[18:19], v[18:19], 0, s[24:25]
	v_lshl_add_u64 v[18:19], v[18:19], 0, v[0:1]
	v_lshl_add_u64 v[18:19], v[18:19], 0, s[8:9]
	v_cmp_ne_u32_e64 s[40:41], 0, v20
	v_mov_b32_e32 v178, 0
	v_mov_b32_e32 v182, 0
	v_mov_b32_e32 v183, 0
	v_mov_b32_e32 v184, 0
	v_mov_b32_e32 v185, 0
	s_and_saveexec_b64 s[6:7], s[40:41]
	s_cbranch_execz .LBB0_1290
	global_load_dwordx4 v[182:185], v[18:19], off
